# cache-policy hint: nt on the prefetched read-once activation rows of the LN-type phases
# baseline (speedup 1.0000x reference)
; __device__ __forceinline__ int mk_tid(int wv) { return (wv << 6) | lane_now(); }
; #define LAS __attribute__((address_space(3)))
; template <int SRC, int EXTRA, bool OUT8 = false> ...
;     const int tid = mk_tid(wv); const int lane = tid & 63, wave = wv;
;     LAS float* w8s = (LAS float*)lds;
;     LAS unsigned* lcnt = (LAS unsigned*)(lds + 32768);
;     if (EXTRA != 0) { for (int i = tid; i < 8192; i += NT) { const int k = i >> 3, j = i & 7; w8s[j * 1024 + k] = w8[(size_t)k * w8ld + j]; } if (tid < 8) lcnt[tid] = 0u; __syncthreads(); }
;     f32x4 gv[4], bv[4];
; #pragma unroll
;     for (int j = 0; j < 4; ++j) { gv[j] = *(const f32x4*)(g + 256 * j + 4 * lane); bv[j] = *(const f32x4*)(b + 256 * j + 4 * lane); }
;     const int gw = blockIdx.x * NWAVES + wave, NGW = G * NWAVES;
;     for (int row = gw; row < M; row += NGW) {
;         f32x4 v[4];
;         if (SRC == 0) {
; #pragma unroll
;             for (int j = 0; j < 4; ++j) v[j] = *(const f32x4*)(src + (size_t)row * 1024 + 256 * j + 4 * lane);
.LBB0_53:
	s_or_b64 exec, exec, s[12:13]
	v_cmp_gt_i32_e32 vcc, 8, v2
	s_and_saveexec_b64 s[12:13], vcc
	v_lshl_add_u32 v2, v2, 2, 0
	v_mov_b32_e32 v3, 0
	ds_write_b32 v2, v3 offset:32768
	s_or_b64 exec, exec, s[12:13]
	s_lshl_b32 s3, s2, 3
	s_add_i32 s34, s68, s3
	s_cmpk_lt_i32 s34, 0x4000
	s_cselect_b64 s[38:39], -1, 0
	s_cmpk_gt_i32 s34, 0x3fff
	s_waitcnt lgkmcnt(0)
	s_barrier
	s_cbranch_scc1 .LBB0_66
	v_and_b32_e32 v36, 63, v8
	v_lshlrev_b32_e32 v50, 4, v36
	global_load_dwordx4 v[2:5], v50, s[4:5]
	global_load_dwordx4 v[6:9], v50, s[4:5] offset:1024
	global_load_dwordx4 v[10:13], v50, s[8:9]
	global_load_dwordx4 v[14:17], v50, s[8:9] offset:1024
	global_load_dwordx4 v[18:21], v50, s[4:5] offset:2048
	global_load_dwordx4 v[22:25], v50, s[4:5] offset:3072
	global_load_dwordx4 v[26:29], v50, s[8:9] offset:2048
	global_load_dwordx4 v[30:33], v50, s[8:9] offset:3072
	s_add_u32 s3, s6, 0x400000
	s_addc_u32 s44, s7, 0
	s_lshl_b32 s26, s2, 4
	s_lshl_b32 s27, s68, 1
	s_ashr_i32 s35, s34, 31
	s_add_i32 s26, s26, s27
	s_lshl_b32 s45, s33, 4
	s_lshl_b64 s[40:41], s[34:35], 2
	v_lshlrev_b32_e32 v52, 2, v36
	v_mov_b32_e32 v53, 0
	s_add_u32 s28, s28, s40
	v_lshl_add_u64 v[54:55], s[10:11], 0, v[52:53]
	v_lshlrev_b32_e32 v52, 16, v36
	s_addc_u32 s29, s29, s41
	v_lshl_add_u64 v[34:35], s[28:29], 0, v[52:53]
	s_mov_b64 s[28:29], 0x100000
	s_ashr_i32 s31, s30, 31
	v_lshl_add_u64 v[56:57], v[34:35], 0, s[28:29]
	s_lshl_b64 s[28:29], s[30:31], 2
	s_lshl_b64 s[40:41], s[34:35], 11
	s_add_u32 s36, s36, s40
	v_lshlrev_b32_e32 v52, 3, v36
	s_addc_u32 s37, s37, s41
	v_lshl_add_u64 v[34:35], s[36:37], 0, v[52:53]
	s_mov_b64 s[36:37], 0x12500000
	v_lshl_add_u64 v[58:59], v[34:35], 0, s[36:37]
	s_lshl_b64 s[36:37], s[30:31], 11
	s_lshl_b64 s[40:41], s[34:35], 12
	s_add_u32 s22, s22, s40
	v_mov_b32_e32 v51, v53
	s_addc_u32 s23, s23, s41
	v_lshl_add_u64 v[34:35], s[22:23], 0, v[50:51]
	s_mov_b64 s[22:23], 0xc00
	v_cmp_eq_u32_e64 s[4:5], 0, v36
	v_cmp_gt_u32_e64 s[6:7], 8, v36
	v_cmp_eq_u32_e64 s[8:9], 7, v36
	v_cmp_eq_u32_e64 s[10:11], 6, v36
	v_cmp_eq_u32_e64 s[12:13], 5, v36
	v_cmp_eq_u32_e64 s[14:15], 4, v36
	v_cmp_eq_u32_e64 s[16:17], 3, v36
	v_cmp_eq_u32_e64 s[18:19], 2, v36
	v_cmp_eq_u32_e64 s[20:21], 1, v36
	v_lshl_add_u64 v[60:61], v[34:35], 0, s[22:23]
	s_lshl_b64 s[40:41], s[30:31], 12
	v_mov_b32_e32 v51, 0x3727c5ac
	s_mov_b32 s31, 0xf800000
	v_mov_b32_e32 v68, 0x260
	s_movk_i32 s35, 0x7fff
	s_mov_b32 s46, 0xffff0000
	s_mov_b32 s47, 0x3f2aaaab
	v_mov_b32_e32 v69, 0x3ecc95a3
	s_mov_b32 s48, 0x3f317218
	s_mov_b32 s49, 0x7f800000
	s_mov_b32 s50, 0x33800000
	v_mov_b32_e32 v62, 0x3f317218
	v_mov_b32_e32 v70, 0x7f800000
	v_mov_b32_e32 v71, 0x7fc00000
	v_mov_b32_e32 v72, 0xff800000
	s_mov_b32 s51, s34
	global_load_dwordx4 v[200:203], v[60:61], off offset:-3072 nt
	global_load_dwordx4 v[196:199], v[60:61], off offset:-2048 nt
	global_load_dwordx4 v[192:195], v[60:61], off offset:-1024 nt
	global_load_dwordx4 v[188:191], v[60:61], off nt
	s_waitcnt vmcnt(0)
	s_mov_b32 s58, 0xaaaaaaaa
	s_mov_b32 s59, 0xaaaaaaaa
	s_mov_b32 s60, 0xcccccccc
	s_mov_b32 s61, 0xcccccccc
	s_mov_b32 s62, 0xf0f0f0f0
	s_mov_b32 s63, 0xf0f0f0f0
	v_mov_b32_e32 v206, 0
	s_and_saveexec_b64 s[66:67], s[6:7]
	global_load_dword v206, v[54:55], off
	s_or_b64 exec, exec, s[66:67]
	s_waitcnt vmcnt(0)
	s_branch .LBB0_59

; template <int SRC, int EXTRA, bool OUT8 = false> ...
;     ...
;     for (int row = gw; row < M; row += NGW) {
;         f32x4 v[4];
;         if (SRC == 0) {
; #pragma unroll
;             for (int j = 0; j < 4; ++j) v[j] = *(const f32x4*)(src + (size_t)row * 1024 + 256 * j + 4 * lane);
.LBB0_59:
	s_waitcnt vmcnt(1)
	v_mov_b64_e32 v[34:35], v[188:189]
	v_mov_b64_e32 v[36:37], v[190:191]
	v_mov_b64_e32 v[38:39], v[192:193]
	v_mov_b64_e32 v[40:41], v[194:195]
	v_mov_b64_e32 v[42:43], v[196:197]
	v_mov_b64_e32 v[44:45], v[198:199]
	v_mov_b64_e32 v[46:47], v[200:201]
	v_mov_b64_e32 v[48:49], v[202:203]
	s_add_i32 s95, s51, s30
	s_cmpk_lt_i32 s95, 0x4000
	s_cbranch_scc0 .Lrowpf_2726
	v_lshl_add_u64 v[204:205], v[60:61], 0, s[40:41]
	global_load_dwordx4 v[200:203], v[204:205], off offset:-3072 nt
	global_load_dwordx4 v[196:199], v[204:205], off offset:-2048 nt
	global_load_dwordx4 v[192:195], v[204:205], off offset:-1024 nt
	global_load_dwordx4 v[188:191], v[204:205], off nt

; __device__ __forceinline__ int mk_tid(int wv) { return (wv << 6) | lane_now(); }
; #define LAS __attribute__((address_space(3)))
; template <int SRC, int EXTRA, bool OUT8 = false> ...
;     const int tid = mk_tid(wv); const int lane = tid & 63, wave = wv;
;     LAS float* w8s = (LAS float*)lds;
;     LAS unsigned* lcnt = (LAS unsigned*)(lds + 32768);
;     if (EXTRA != 0) { for (int i = tid; i < 8192; i += NT) { const int k = i >> 3, j = i & 7; w8s[j * 1024 + k] = w8[(size_t)k * w8ld + j]; } if (tid < 8) lcnt[tid] = 0u; __syncthreads(); }
;     f32x4 gv[4], bv[4];
; #pragma unroll
;     for (int j = 0; j < 4; ++j) { gv[j] = *(const f32x4*)(g + 256 * j + 4 * lane); bv[j] = *(const f32x4*)(b + 256 * j + 4 * lane); }
;     const int gw = blockIdx.x * NWAVES + wave, NGW = G * NWAVES;
;     for (int row = gw; row < M; row += NGW) {
;         f32x4 v[4];
;         if (SRC == 0) {
; #pragma unroll
;             for (int j = 0; j < 4; ++j) v[j] = *(const f32x4*)(src + (size_t)row * 1024 + 256 * j + 4 * lane);
.LBB0_837:
	s_or_b64 exec, exec, s[4:5]
	s_waitcnt lgkmcnt(0)
	v_cndmask_b32_e64 v0, 0, 1, s[38:39]
	s_mov_b64 s[10:11], s[0:1]
	s_mov_b64 s[16:17], s[0:1]
	s_mov_b64 s[18:19], s[0:1]
	s_mov_b64 s[14:15], s[0:1]
	s_mov_b64 s[12:13], s[0:1]
	v_cmp_ne_u32_e64 s[4:5], 1, v0
	s_andn2_b64 vcc, exec, s[38:39]
	s_barrier
	v_mbcnt_lo_u32_b32 v0, -1, 0
	v_mbcnt_hi_u32_b32 v0, -1, v0
	s_cbranch_vccnz .LBB0_842
	s_load_dwordx2 s[20:21], s[16:17], 0x68
	s_load_dwordx2 s[22:23], s[18:19], 0x70
	v_and_b32_e32 v33, 63, v0
	v_lshlrev_b32_e32 v32, 4, v33
	v_lshlrev_b32_e32 v48, 2, v33
	v_mov_b32_e32 v49, 0
	s_waitcnt lgkmcnt(0)
	global_load_dwordx4 v[0:3], v32, s[20:21]
	global_load_dwordx4 v[4:7], v32, s[20:21] offset:1024
	global_load_dwordx4 v[8:11], v32, s[22:23]
	global_load_dwordx4 v[12:15], v32, s[22:23] offset:1024
	global_load_dwordx4 v[16:19], v32, s[20:21] offset:2048
	global_load_dwordx4 v[20:23], v32, s[20:21] offset:3072
	global_load_dwordx4 v[24:27], v32, s[22:23] offset:2048
	global_load_dwordx4 v[28:31], v32, s[22:23] offset:3072
	s_load_dwordx2 s[16:17], s[14:15], 0xc0
	s_load_dwordx2 s[18:19], s[10:11], 0xc0
	v_cmp_eq_u32_e64 s[10:11], 0, v33
	s_load_dwordx2 s[12:13], s[12:13], 0xc0
	v_mov_b32_e32 v33, v49
	s_waitcnt lgkmcnt(0)
	s_add_u32 s3, s16, 0x400000
	s_addc_u32 s20, s17, 0
	s_lshl_b32 s14, s2, 4
	s_lshl_b32 s15, s68, 1
	s_ashr_i32 s35, s34, 31
	s_add_i32 s14, s14, s15
	s_lshl_b32 s21, s33, 4
	s_lshl_b64 s[16:17], s[34:35], 10
	s_add_u32 s12, s12, s16
	s_addc_u32 s13, s13, s17
	v_lshl_add_u64 v[34:35], s[12:13], 0, v[48:49]
	s_mov_b64 s[12:13], 0x12500300
	s_ashr_i32 s31, s30, 31
	v_lshl_add_u64 v[50:51], v[34:35], 0, s[12:13]
	s_lshl_b64 s[16:17], s[30:31], 10
	s_lshl_b64 s[12:13], s[34:35], 12
	s_add_u32 s12, s18, s12
	s_addc_u32 s13, s19, s13
	v_lshl_add_u64 v[32:33], s[12:13], 0, v[32:33]
	s_mov_b64 s[12:13], 0x28500c00
	v_lshl_add_u64 v[52:53], v[32:33], 0, s[12:13]
	s_lshl_b64 s[18:19], s[30:31], 12
	v_mov_b32_e32 v54, 0x3727c5ac
	s_mov_b32 s22, 0xf800000
	v_mov_b32_e32 v55, 0x260
	s_mov_b32 s23, s34
	global_load_dwordx4 v[200:203], v[52:53], off offset:-3072 nt
	global_load_dwordx4 v[196:199], v[52:53], off offset:-2048 nt
	global_load_dwordx4 v[192:195], v[52:53], off offset:-1024 nt
	global_load_dwordx4 v[188:191], v[52:53], off nt
	s_waitcnt vmcnt(0)
	s_branch .LBB0_840

; template <int SRC, int EXTRA, bool OUT8 = false> ...
;     ...
;     for (int row = gw; row < M; row += NGW) {
;         f32x4 v[4];
;         if (SRC == 0) {
; #pragma unroll
;             for (int j = 0; j < 4; ++j) v[j] = *(const f32x4*)(src + (size_t)row * 1024 + 256 * j + 4 * lane);
.LBB0_840:
	s_waitcnt vmcnt(4)
	v_mov_b64_e32 v[32:33], v[188:189]
	v_mov_b64_e32 v[34:35], v[190:191]
	v_mov_b64_e32 v[36:37], v[192:193]
	v_mov_b64_e32 v[38:39], v[194:195]
	v_mov_b64_e32 v[40:41], v[196:197]
	v_mov_b64_e32 v[42:43], v[198:199]
	v_mov_b64_e32 v[44:45], v[200:201]
	v_mov_b64_e32 v[46:47], v[202:203]
	s_add_i32 s95, s23, s30
	s_cmpk_lt_i32 s95, 0x4000
	s_cbranch_scc0 .Lrowpf_22491
	v_lshl_add_u64 v[204:205], v[52:53], 0, s[18:19]
	global_load_dwordx4 v[200:203], v[204:205], off offset:-3072 nt
	global_load_dwordx4 v[196:199], v[204:205], off offset:-2048 nt
	global_load_dwordx4 v[192:195], v[204:205], off offset:-1024 nt
	global_load_dwordx4 v[188:191], v[204:205], off nt

; __device__ __forceinline__ int mk_tid(int wv) { return (wv << 6) | lane_now(); }
; #define LAS __attribute__((address_space(3)))
; template <int SRC, int EXTRA, bool OUT8 = false> ...
;     const int tid = mk_tid(wv); const int lane = tid & 63, wave = wv;
;     LAS float* w8s = (LAS float*)lds;
;     LAS unsigned* lcnt = (LAS unsigned*)(lds + 32768);
;     if (EXTRA != 0) { for (int i = tid; i < 8192; i += NT) { const int k = i >> 3, j = i & 7; w8s[j * 1024 + k] = w8[(size_t)k * w8ld + j]; } if (tid < 8) lcnt[tid] = 0u; __syncthreads(); }
;     f32x4 gv[4], bv[4];
; #pragma unroll
;     for (int j = 0; j < 4; ++j) { gv[j] = *(const f32x4*)(g + 256 * j + 4 * lane); bv[j] = *(const f32x4*)(b + 256 * j + 4 * lane); }
;     const int gw = blockIdx.x * NWAVES + wave, NGW = G * NWAVES;
;     for (int row = gw; row < M; row += NGW) {
;         f32x4 v[4];
;         if (SRC == 0) {
; #pragma unroll
;             for (int j = 0; j < 4; ++j) v[j] = *(const f32x4*)(src + (size_t)row * 1024 + 256 * j + 4 * lane);
.LBB0_1051:
	s_or_b64 exec, exec, s[18:19]
	v_cmp_gt_i32_e32 vcc, 8, v0
	s_and_saveexec_b64 s[18:19], vcc
	v_lshl_add_u32 v0, v0, 2, 0
	v_mov_b32_e32 v1, 0
	ds_write_b32 v0, v1 offset:32768
	s_or_b64 exec, exec, s[18:19]
	s_and_b64 vcc, exec, s[4:5]
	s_waitcnt lgkmcnt(0)
	s_barrier
	s_cbranch_vccnz .LBB0_1064
	v_and_b32_e32 v34, 63, v6
	v_lshlrev_b32_e32 v48, 4, v34
	global_load_dwordx4 v[0:3], v48, s[10:11]
	global_load_dwordx4 v[4:7], v48, s[10:11] offset:1024
	global_load_dwordx4 v[8:11], v48, s[14:15]
	global_load_dwordx4 v[12:15], v48, s[14:15] offset:1024
	global_load_dwordx4 v[16:19], v48, s[10:11] offset:2048
	global_load_dwordx4 v[20:23], v48, s[10:11] offset:3072
	global_load_dwordx4 v[24:27], v48, s[14:15] offset:2048
	global_load_dwordx4 v[28:31], v48, s[14:15] offset:3072
	s_add_u32 s3, s12, 0x400000
	s_addc_u32 s40, s13, 0
	s_lshl_b32 s31, s2, 4
	s_lshl_b32 s35, s68, 1
	s_add_i32 s44, s31, s35
	s_ashr_i32 s35, s34, 31
	s_lshl_b32 s41, s33, 4
	s_lshl_b64 s[42:43], s[34:35], 2
	v_lshlrev_b32_e32 v50, 2, v34
	v_mov_b32_e32 v51, 0
	s_add_u32 s42, s46, s42
	v_lshl_add_u64 v[52:53], s[16:17], 0, v[50:51]
	v_lshlrev_b32_e32 v50, 16, v34
	s_addc_u32 s43, s47, s43
	v_lshl_add_u64 v[32:33], s[42:43], 0, v[50:51]
	s_mov_b64 s[42:43], 0x100000
	s_ashr_i32 s31, s30, 31
	v_lshl_add_u64 v[54:55], v[32:33], 0, s[42:43]
	s_lshl_b64 s[46:47], s[30:31], 2
	s_lshl_b64 s[42:43], s[34:35], 11
	s_add_u32 s42, s48, s42
	v_lshlrev_b32_e32 v50, 3, v34
	s_addc_u32 s43, s49, s43
	v_lshl_add_u64 v[32:33], s[42:43], 0, v[50:51]
	s_mov_b64 s[42:43], 0x12500600
	v_lshl_add_u64 v[56:57], v[32:33], 0, s[42:43]
	s_lshl_b64 s[48:49], s[30:31], 11
	s_lshl_b64 s[42:43], s[34:35], 12
	s_add_u32 s28, s28, s42
	v_mov_b32_e32 v49, v51
	s_addc_u32 s29, s29, s43
	v_lshl_add_u64 v[32:33], s[28:29], 0, v[48:49]
	s_mov_b64 s[28:29], 0x28500c00
	v_cmp_eq_u32_e64 s[10:11], 0, v34
	v_cmp_gt_u32_e64 s[12:13], 8, v34
	v_cmp_eq_u32_e64 s[14:15], 7, v34
	v_cmp_eq_u32_e64 s[16:17], 6, v34
	v_cmp_eq_u32_e64 s[18:19], 5, v34
	v_cmp_eq_u32_e64 s[20:21], 4, v34
	v_cmp_eq_u32_e64 s[22:23], 3, v34
	v_cmp_eq_u32_e64 s[24:25], 2, v34
	v_cmp_eq_u32_e64 s[26:27], 1, v34
	v_lshl_add_u64 v[58:59], v[32:33], 0, s[28:29]
	s_lshl_b64 s[50:51], s[30:31], 12
	v_mov_b32_e32 v49, 0x3727c5ac
	s_mov_b32 s31, 0xf800000
	v_mov_b32_e32 v66, 0x260
	s_movk_i32 s35, 0x7fff
	s_mov_b32 s42, 0xffff0000
	s_mov_b32 s43, 0x3f2aaaab
	v_mov_b32_e32 v67, 0x3ecc95a3
	s_mov_b32 s54, 0x3f317218
	s_mov_b32 s55, 0x7f800000
	s_mov_b32 s56, 0x33800000
	v_mov_b32_e32 v60, 0x3f317218
	v_mov_b32_e32 v68, 0x7f800000
	v_mov_b32_e32 v69, 0x7fc00000
	v_mov_b32_e32 v70, 0xff800000
	s_mov_b32 s57, s34
	global_load_dwordx4 v[200:203], v[58:59], off offset:-3072 nt
	global_load_dwordx4 v[196:199], v[58:59], off offset:-2048 nt
	global_load_dwordx4 v[192:195], v[58:59], off offset:-1024 nt
	global_load_dwordx4 v[188:191], v[58:59], off nt
	s_waitcnt vmcnt(0)
	s_mov_b32 s58, 0xaaaaaaaa
	s_mov_b32 s59, 0xaaaaaaaa
	s_mov_b32 s60, 0xcccccccc
	s_mov_b32 s61, 0xcccccccc
	s_mov_b32 s62, 0xf0f0f0f0
	s_mov_b32 s63, 0xf0f0f0f0
	v_mov_b32_e32 v206, 0
	s_and_saveexec_b64 s[66:67], s[12:13]
	global_load_dword v206, v[52:53], off offset:32
	s_or_b64 exec, exec, s[66:67]
	s_waitcnt vmcnt(0)
	s_branch .LBB0_1057

; template <int SRC, int EXTRA, bool OUT8 = false> ...
;     ...
;     for (int row = gw; row < M; row += NGW) {
;         f32x4 v[4];
;         if (SRC == 0) {
; #pragma unroll
;             for (int j = 0; j < 4; ++j) v[j] = *(const f32x4*)(src + (size_t)row * 1024 + 256 * j + 4 * lane);
.LBB0_1057:
	s_waitcnt vmcnt(1)
	v_mov_b64_e32 v[32:33], v[188:189]
	v_mov_b64_e32 v[34:35], v[190:191]
	v_mov_b64_e32 v[36:37], v[192:193]
	v_mov_b64_e32 v[38:39], v[194:195]
	v_mov_b64_e32 v[40:41], v[196:197]
	v_mov_b64_e32 v[42:43], v[198:199]
	v_mov_b64_e32 v[44:45], v[200:201]
	v_mov_b64_e32 v[46:47], v[202:203]
	s_add_i32 s95, s57, s30
	s_cmpk_lt_i32 s95, 0x4000
	s_cbranch_scc0 .Lrowpf_27526
	v_lshl_add_u64 v[204:205], v[58:59], 0, s[50:51]
	global_load_dwordx4 v[200:203], v[204:205], off offset:-3072 nt
	global_load_dwordx4 v[196:199], v[204:205], off offset:-2048 nt
	global_load_dwordx4 v[192:195], v[204:205], off offset:-1024 nt
	global_load_dwordx4 v[188:191], v[204:205], off nt

; __device__ __forceinline__ int mk_tid(int wv) { return (wv << 6) | lane_now(); }
; #define LAS __attribute__((address_space(3)))
; template <int SRC, int EXTRA, bool OUT8 = false> ...
;     const int tid = mk_tid(wv); const int lane = tid & 63, wave = wv;
;     LAS float* w8s = (LAS float*)lds;
;     LAS unsigned* lcnt = (LAS unsigned*)(lds + 32768);
;     if (EXTRA != 0) { for (int i = tid; i < 8192; i += NT) { const int k = i >> 3, j = i & 7; w8s[j * 1024 + k] = w8[(size_t)k * w8ld + j]; } if (tid < 8) lcnt[tid] = 0u; __syncthreads(); }
;     f32x4 gv[4], bv[4];
; #pragma unroll
;     for (int j = 0; j < 4; ++j) { gv[j] = *(const f32x4*)(g + 256 * j + 4 * lane); bv[j] = *(const f32x4*)(b + 256 * j + 4 * lane); }
;     const int gw = blockIdx.x * NWAVES + wave, NGW = G * NWAVES;
;     for (int row = gw; row < M; row += NGW) {
;         f32x4 v[4];
;         if (SRC == 0) {
; #pragma unroll
;             for (int j = 0; j < 4; ++j) v[j] = *(const f32x4*)(src + (size_t)row * 1024 + 256 * j + 4 * lane);
.LBB0_1891:
	s_or_b64 exec, exec, s[8:9]
	v_cmp_gt_i32_e64 s[8:9], 8, v48
	v_lshl_add_u32 v49, v48, 2, 0
	s_and_saveexec_b64 s[24:25], s[8:9]
	v_mov_b32_e32 v0, 0
	ds_write_b32 v49, v0 offset:32768
	s_or_b64 exec, exec, s[24:25]
	s_and_b64 vcc, exec, s[4:5]
	s_waitcnt lgkmcnt(0)
	s_barrier
	s_cbranch_vccnz .LBB0_1900
	v_and_b32_e32 v38, 63, v4
	v_lshlrev_b32_e32 v50, 4, v38
	v_mov_b32_e32 v51, 0
	v_lshl_add_u64 v[0:1], s[20:21], 0, v[50:51]
	s_mov_b64 s[20:21], 0x1000
	v_lshl_add_u64 v[32:33], v[0:1], 0, s[20:21]
	v_add_co_u32_e32 v0, vcc, 0x1000, v0
	v_lshl_add_u64 v[4:5], s[22:23], 0, v[50:51]
	s_nop 0
	v_addc_co_u32_e32 v1, vcc, 0, v1, vcc
	v_add_co_u32_e32 v36, vcc, 0x1000, v4
	v_lshl_add_u64 v[34:35], v[4:5], 0, s[20:21]
	s_nop 0
	v_addc_co_u32_e32 v37, vcc, 0, v5, vcc
	global_load_dwordx4 v[0:3], v[0:1], off
	s_nop 0
	global_load_dwordx4 v[4:7], v[36:37], off
	global_load_dwordx4 v[8:11], v[32:33], off offset:1024
	global_load_dwordx4 v[12:15], v[32:33], off offset:2048
	global_load_dwordx4 v[16:19], v[34:35], off offset:1024
	global_load_dwordx4 v[20:23], v[34:35], off offset:2048
	global_load_dwordx4 v[24:27], v[32:33], off offset:3072
	global_load_dwordx4 v[28:31], v[34:35], off offset:3072
	s_add_u32 s3, s10, 0x400000
	s_addc_u32 s50, s11, 0
	s_add_u32 s51, s18, 0x340000
	s_addc_u32 s52, s19, 0
	s_lshl_b32 s18, s2, 4
	s_lshl_b32 s19, s68, 1
	s_ashr_i32 s35, s34, 31
	s_add_i32 s38, s18, s19
	s_lshl_b32 s53, s33, 4
	s_lshl_b64 s[18:19], s[34:35], 2
	s_add_u32 s16, s16, s18
	s_addc_u32 s17, s17, s19
	s_add_u32 s40, s16, 0x300000
	s_addc_u32 s41, s17, 0
	s_ashr_i32 s31, s30, 31
	s_lshl_b64 s[42:43], s[30:31], 2
	s_lshl_b64 s[16:17], s[34:35], 11
	s_add_u32 s14, s14, s16
	v_lshlrev_b32_e32 v32, 3, v38
	v_mov_b32_e32 v33, v51
	s_addc_u32 s15, s15, s17
	v_lshl_add_u64 v[32:33], s[14:15], 0, v[32:33]
	s_mov_b64 s[14:15], 0x12500600
	v_lshl_add_u64 v[52:53], v[32:33], 0, s[14:15]
	s_lshl_b64 s[44:45], s[30:31], 11
	s_lshl_b64 s[14:15], s[34:35], 12
	s_add_u32 s12, s12, s14
	s_addc_u32 s13, s13, s15
	v_lshl_add_u64 v[32:33], s[12:13], 0, v[50:51]
	s_mov_b64 s[12:13], 0x28500c00
	v_cmp_eq_u32_e64 s[10:11], 0, v38
	v_lshl_add_u64 v[54:55], v[32:33], 0, s[12:13]
	s_lshl_b64 s[46:47], s[30:31], 12
	v_mov_b32_e32 v61, 0x3727c5ac
	s_mov_b32 s31, 0xf800000
	v_mov_b32_e32 v62, 0x260
	s_movk_i32 s35, 0x7fff
	s_mov_b32 s54, 0xffff0000
	v_mov_b32_e32 v63, 1
	s_mov_b32 s55, 0xff800000
	v_mov_b32_e32 v64, 0xff800000
	s_mov_b32 s56, s34
	global_load_dwordx4 v[200:203], v[54:55], off offset:-3072 nt
	global_load_dwordx4 v[196:199], v[54:55], off offset:-2048 nt
	global_load_dwordx4 v[192:195], v[54:55], off offset:-1024 nt
	global_load_dwordx4 v[188:191], v[54:55], off nt
	s_waitcnt vmcnt(0)
	s_mov_b32 s58, 0xaaaaaaaa
	s_mov_b32 s59, 0xaaaaaaaa
	s_mov_b32 s60, 0xcccccccc
	s_mov_b32 s61, 0xcccccccc
	s_mov_b32 s62, 0xf0f0f0f0
	s_mov_b32 s63, 0xf0f0f0f0
	s_branch .LBB0_1896

; template <int SRC, int EXTRA, bool OUT8 = false> ...
;     ...
;     for (int row = gw; row < M; row += NGW) {
;         f32x4 v[4];
;         if (SRC == 0) {
; #pragma unroll
;             for (int j = 0; j < 4; ++j) v[j] = *(const f32x4*)(src + (size_t)row * 1024 + 256 * j + 4 * lane);
.LBB0_1896:
	s_waitcnt vmcnt(2)
	v_mov_b64_e32 v[32:33], v[188:189]
	v_mov_b64_e32 v[34:35], v[190:191]
	v_mov_b64_e32 v[36:37], v[192:193]
	v_mov_b64_e32 v[38:39], v[194:195]
	v_mov_b64_e32 v[40:41], v[196:197]
	v_mov_b64_e32 v[42:43], v[198:199]
	v_mov_b64_e32 v[44:45], v[200:201]
	v_mov_b64_e32 v[46:47], v[202:203]
	s_add_i32 s95, s56, s30
	s_cmpk_lt_i32 s95, 0x4000
	s_cbranch_scc0 .Lrowpf_48034
	v_lshl_add_u64 v[204:205], v[54:55], 0, s[46:47]
	global_load_dwordx4 v[200:203], v[204:205], off offset:-3072 nt
	global_load_dwordx4 v[196:199], v[204:205], off offset:-2048 nt
	global_load_dwordx4 v[192:195], v[204:205], off offset:-1024 nt
	global_load_dwordx4 v[188:191], v[204:205], off nt
